# GEMM K-loop heads aligned to 64 bytes (instruction-fetch placement of the loop entry)
# speedup vs baseline: 1.0025x; 1.0025x over previous
.LBB0_304:
	s_add_u32 s4, s4, 0x40080
	s_addc_u32 s5, s5, 0
	s_add_u32 s23, s30, 0x100
	v_mov_b32_e32 v0, 0
	s_addc_u32 s25, s31, 0
	s_mov_b32 s51, -2
	v_mov_b32_e32 v1, v0
	v_mov_b32_e32 v2, v0
	v_mov_b32_e32 v3, v0
	v_mov_b32_e32 v4, v0
	v_mov_b32_e32 v5, v0
	v_mov_b32_e32 v6, v0
	v_mov_b32_e32 v7, v0
	v_mov_b32_e32 v16, v0
	v_mov_b32_e32 v17, v0
	v_mov_b32_e32 v18, v0
	v_mov_b32_e32 v19, v0
	v_mov_b32_e32 v20, v0
	v_mov_b32_e32 v21, v0
	v_mov_b32_e32 v22, v0
	v_mov_b32_e32 v23, v0
	v_mov_b32_e32 v32, v0
	v_mov_b32_e32 v33, v0
	v_mov_b32_e32 v34, v0
	v_mov_b32_e32 v35, v0
	v_mov_b32_e32 v36, v0
	v_mov_b32_e32 v37, v0
	v_mov_b32_e32 v38, v0
	v_mov_b32_e32 v39, v0
	v_mov_b32_e32 v50, v0
	v_mov_b32_e32 v51, v0
	v_mov_b32_e32 v52, v0
	v_mov_b32_e32 v53, v0
	v_mov_b32_e32 v54, v0
	v_mov_b32_e32 v55, v0
	v_mov_b32_e32 v56, v0
	v_mov_b32_e32 v57, v0
	v_mov_b32_e32 v8, v0
	v_mov_b32_e32 v9, v0
	v_mov_b32_e32 v10, v0
	v_mov_b32_e32 v11, v0
	v_mov_b32_e32 v12, v0
	v_mov_b32_e32 v13, v0
	v_mov_b32_e32 v14, v0
	v_mov_b32_e32 v15, v0
	v_mov_b32_e32 v24, v0
	v_mov_b32_e32 v25, v0
	v_mov_b32_e32 v26, v0
	v_mov_b32_e32 v27, v0
	v_mov_b32_e32 v28, v0
	v_mov_b32_e32 v29, v0
	v_mov_b32_e32 v30, v0
	v_mov_b32_e32 v31, v0
	v_mov_b32_e32 v40, v0
	v_mov_b32_e32 v41, v0
	v_mov_b32_e32 v42, v0
	v_mov_b32_e32 v43, v0
	v_mov_b32_e32 v44, v0
	v_mov_b32_e32 v45, v0
	v_mov_b32_e32 v46, v0
	v_mov_b32_e32 v47, v0
	v_mov_b32_e32 v58, v0
	v_mov_b32_e32 v59, v0
	v_mov_b32_e32 v60, v0
	v_mov_b32_e32 v61, v0
	v_mov_b32_e32 v62, v0
	v_mov_b32_e32 v63, v0
	v_mov_b32_e32 v64, v0
	v_mov_b32_e32 v65, v0
	v_mov_b32_e32 v66, v0
	v_mov_b32_e32 v67, v0
	v_mov_b32_e32 v68, v0
	v_mov_b32_e32 v69, v0
	v_mov_b32_e32 v70, v0
	v_mov_b32_e32 v71, v0
	v_mov_b32_e32 v72, v0
	v_mov_b32_e32 v73, v0
	v_mov_b32_e32 v82, v0
	v_mov_b32_e32 v83, v0
	v_mov_b32_e32 v84, v0
	v_mov_b32_e32 v85, v0
	v_mov_b32_e32 v86, v0
	v_mov_b32_e32 v87, v0
	v_mov_b32_e32 v88, v0
	v_mov_b32_e32 v89, v0
	v_mov_b32_e32 v98, v0
	v_mov_b32_e32 v99, v0
	v_mov_b32_e32 v100, v0
	v_mov_b32_e32 v101, v0
	v_mov_b32_e32 v102, v0
	v_mov_b32_e32 v103, v0
	v_mov_b32_e32 v104, v0
	v_mov_b32_e32 v105, v0
	v_mov_b32_e32 v114, v0
	v_mov_b32_e32 v115, v0
	v_mov_b32_e32 v116, v0
	v_mov_b32_e32 v117, v0
	v_mov_b32_e32 v118, v0
	v_mov_b32_e32 v119, v0
	v_mov_b32_e32 v120, v0
	v_mov_b32_e32 v121, v0
	v_mov_b32_e32 v74, v0
	v_mov_b32_e32 v75, v0
	v_mov_b32_e32 v76, v0
	v_mov_b32_e32 v77, v0
	v_mov_b32_e32 v78, v0
	v_mov_b32_e32 v79, v0
	v_mov_b32_e32 v80, v0
	v_mov_b32_e32 v81, v0
	v_mov_b32_e32 v90, v0
	v_mov_b32_e32 v91, v0
	v_mov_b32_e32 v92, v0
	v_mov_b32_e32 v93, v0
	v_mov_b32_e32 v94, v0
	v_mov_b32_e32 v95, v0
	v_mov_b32_e32 v96, v0
	v_mov_b32_e32 v97, v0
	v_mov_b32_e32 v106, v0
	v_mov_b32_e32 v107, v0
	v_mov_b32_e32 v108, v0
	v_mov_b32_e32 v109, v0
	v_mov_b32_e32 v110, v0
	v_mov_b32_e32 v111, v0
	v_mov_b32_e32 v112, v0
	v_mov_b32_e32 v113, v0
	v_mov_b32_e32 v122, v0
	v_mov_b32_e32 v123, v0
	v_mov_b32_e32 v124, v0
	v_mov_b32_e32 v125, v0
	v_mov_b32_e32 v126, v0
	v_mov_b32_e32 v127, v0
	v_mov_b32_e32 v128, v0
	v_mov_b32_e32 v129, v0
	v_add_u32_e32 v133, 0x10000, v141
	.p2align	6

.LBB0_640:
	s_add_u32 s5, s24, 0x100
	v_mov_b32_e32 v0, 0
	s_addc_u32 s48, s25, 0
	s_mov_b32 s49, -2
	v_mov_b32_e32 v1, v0
	v_mov_b32_e32 v2, v0
	v_mov_b32_e32 v3, v0
	v_mov_b32_e32 v4, v0
	v_mov_b32_e32 v5, v0
	v_mov_b32_e32 v6, v0
	v_mov_b32_e32 v7, v0
	v_mov_b32_e32 v8, v0
	v_mov_b32_e32 v9, v0
	v_mov_b32_e32 v10, v0
	v_mov_b32_e32 v11, v0
	v_mov_b32_e32 v12, v0
	v_mov_b32_e32 v13, v0
	v_mov_b32_e32 v14, v0
	v_mov_b32_e32 v15, v0
	v_mov_b32_e32 v24, v0
	v_mov_b32_e32 v25, v0
	v_mov_b32_e32 v26, v0
	v_mov_b32_e32 v27, v0
	v_mov_b32_e32 v28, v0
	v_mov_b32_e32 v29, v0
	v_mov_b32_e32 v30, v0
	v_mov_b32_e32 v31, v0
	v_mov_b32_e32 v40, v0
	v_mov_b32_e32 v41, v0
	v_mov_b32_e32 v42, v0
	v_mov_b32_e32 v43, v0
	v_mov_b32_e32 v44, v0
	v_mov_b32_e32 v45, v0
	v_mov_b32_e32 v46, v0
	v_mov_b32_e32 v47, v0
	v_mov_b32_e32 v16, v0
	v_mov_b32_e32 v17, v0
	v_mov_b32_e32 v18, v0
	v_mov_b32_e32 v19, v0
	v_mov_b32_e32 v20, v0
	v_mov_b32_e32 v21, v0
	v_mov_b32_e32 v22, v0
	v_mov_b32_e32 v23, v0
	v_mov_b32_e32 v32, v0
	v_mov_b32_e32 v33, v0
	v_mov_b32_e32 v34, v0
	v_mov_b32_e32 v35, v0
	v_mov_b32_e32 v36, v0
	v_mov_b32_e32 v37, v0
	v_mov_b32_e32 v38, v0
	v_mov_b32_e32 v39, v0
	v_mov_b32_e32 v50, v0
	v_mov_b32_e32 v51, v0
	v_mov_b32_e32 v52, v0
	v_mov_b32_e32 v53, v0
	v_mov_b32_e32 v54, v0
	v_mov_b32_e32 v55, v0
	v_mov_b32_e32 v56, v0
	v_mov_b32_e32 v57, v0
	v_mov_b32_e32 v58, v0
	v_mov_b32_e32 v59, v0
	v_mov_b32_e32 v60, v0
	v_mov_b32_e32 v61, v0
	v_mov_b32_e32 v62, v0
	v_mov_b32_e32 v63, v0
	v_mov_b32_e32 v64, v0
	v_mov_b32_e32 v65, v0
	v_mov_b32_e32 v66, v0
	v_mov_b32_e32 v67, v0
	v_mov_b32_e32 v68, v0
	v_mov_b32_e32 v69, v0
	v_mov_b32_e32 v70, v0
	v_mov_b32_e32 v71, v0
	v_mov_b32_e32 v72, v0
	v_mov_b32_e32 v73, v0
	v_mov_b32_e32 v74, v0
	v_mov_b32_e32 v75, v0
	v_mov_b32_e32 v76, v0
	v_mov_b32_e32 v77, v0
	v_mov_b32_e32 v78, v0
	v_mov_b32_e32 v79, v0
	v_mov_b32_e32 v80, v0
	v_mov_b32_e32 v81, v0
	v_mov_b32_e32 v86, v0
	v_mov_b32_e32 v87, v0
	v_mov_b32_e32 v88, v0
	v_mov_b32_e32 v89, v0
	v_mov_b32_e32 v94, v0
	v_mov_b32_e32 v95, v0
	v_mov_b32_e32 v96, v0
	v_mov_b32_e32 v97, v0
	v_mov_b32_e32 v102, v0
	v_mov_b32_e32 v103, v0
	v_mov_b32_e32 v104, v0
	v_mov_b32_e32 v105, v0
	v_mov_b32_e32 v110, v0
	v_mov_b32_e32 v111, v0
	v_mov_b32_e32 v112, v0
	v_mov_b32_e32 v113, v0
	v_mov_b32_e32 v82, v0
	v_mov_b32_e32 v83, v0
	v_mov_b32_e32 v84, v0
	v_mov_b32_e32 v85, v0
	v_mov_b32_e32 v90, v0
	v_mov_b32_e32 v91, v0
	v_mov_b32_e32 v92, v0
	v_mov_b32_e32 v93, v0
	v_mov_b32_e32 v98, v0
	v_mov_b32_e32 v99, v0
	v_mov_b32_e32 v100, v0
	v_mov_b32_e32 v101, v0
	v_mov_b32_e32 v106, v0
	v_mov_b32_e32 v107, v0
	v_mov_b32_e32 v108, v0
	v_mov_b32_e32 v109, v0
	v_mov_b32_e32 v114, v0
	v_mov_b32_e32 v115, v0
	v_mov_b32_e32 v116, v0
	v_mov_b32_e32 v117, v0
	v_mov_b32_e32 v118, v0
	v_mov_b32_e32 v119, v0
	v_mov_b32_e32 v120, v0
	v_mov_b32_e32 v121, v0
	v_mov_b32_e32 v122, v0
	v_mov_b32_e32 v123, v0
	v_mov_b32_e32 v124, v0
	v_mov_b32_e32 v125, v0
	v_mov_b32_e32 v126, v0
	v_mov_b32_e32 v127, v0
	v_mov_b32_e32 v128, v0
	v_mov_b32_e32 v129, v0
	v_add_u32_e32 v131, 0x10000, v143
	.p2align	6

.LBB0_821:
	s_add_u32 s39, s12, 0x100
	v_mov_b32_e32 v0, 0
	s_addc_u32 s40, s13, 0
	s_mov_b32 s41, -2
	v_mov_b32_e32 v1, v0
	v_mov_b32_e32 v2, v0
	v_mov_b32_e32 v3, v0
	v_mov_b32_e32 v4, v0
	v_mov_b32_e32 v5, v0
	v_mov_b32_e32 v6, v0
	v_mov_b32_e32 v7, v0
	v_mov_b32_e32 v16, v0
	v_mov_b32_e32 v17, v0
	v_mov_b32_e32 v18, v0
	v_mov_b32_e32 v19, v0
	v_mov_b32_e32 v20, v0
	v_mov_b32_e32 v21, v0
	v_mov_b32_e32 v22, v0
	v_mov_b32_e32 v23, v0
	v_mov_b32_e32 v32, v0
	v_mov_b32_e32 v33, v0
	v_mov_b32_e32 v34, v0
	v_mov_b32_e32 v35, v0
	v_mov_b32_e32 v36, v0
	v_mov_b32_e32 v37, v0
	v_mov_b32_e32 v38, v0
	v_mov_b32_e32 v39, v0
	v_mov_b32_e32 v50, v0
	v_mov_b32_e32 v51, v0
	v_mov_b32_e32 v52, v0
	v_mov_b32_e32 v53, v0
	v_mov_b32_e32 v54, v0
	v_mov_b32_e32 v55, v0
	v_mov_b32_e32 v56, v0
	v_mov_b32_e32 v57, v0
	v_mov_b32_e32 v8, v0
	v_mov_b32_e32 v9, v0
	v_mov_b32_e32 v10, v0
	v_mov_b32_e32 v11, v0
	v_mov_b32_e32 v12, v0
	v_mov_b32_e32 v13, v0
	v_mov_b32_e32 v14, v0
	v_mov_b32_e32 v15, v0
	v_mov_b32_e32 v24, v0
	v_mov_b32_e32 v25, v0
	v_mov_b32_e32 v26, v0
	v_mov_b32_e32 v27, v0
	v_mov_b32_e32 v28, v0
	v_mov_b32_e32 v29, v0
	v_mov_b32_e32 v30, v0
	v_mov_b32_e32 v31, v0
	v_mov_b32_e32 v40, v0
	v_mov_b32_e32 v41, v0
	v_mov_b32_e32 v42, v0
	v_mov_b32_e32 v43, v0
	v_mov_b32_e32 v44, v0
	v_mov_b32_e32 v45, v0
	v_mov_b32_e32 v46, v0
	v_mov_b32_e32 v47, v0
	v_mov_b32_e32 v58, v0
	v_mov_b32_e32 v59, v0
	v_mov_b32_e32 v60, v0
	v_mov_b32_e32 v61, v0
	v_mov_b32_e32 v62, v0
	v_mov_b32_e32 v63, v0
	v_mov_b32_e32 v64, v0
	v_mov_b32_e32 v65, v0
	v_mov_b32_e32 v66, v0
	v_mov_b32_e32 v67, v0
	v_mov_b32_e32 v68, v0
	v_mov_b32_e32 v69, v0
	v_mov_b32_e32 v70, v0
	v_mov_b32_e32 v71, v0
	v_mov_b32_e32 v72, v0
	v_mov_b32_e32 v73, v0
	v_mov_b32_e32 v82, v0
	v_mov_b32_e32 v83, v0
	v_mov_b32_e32 v84, v0
	v_mov_b32_e32 v85, v0
	v_mov_b32_e32 v86, v0
	v_mov_b32_e32 v87, v0
	v_mov_b32_e32 v88, v0
	v_mov_b32_e32 v89, v0
	v_mov_b32_e32 v98, v0
	v_mov_b32_e32 v99, v0
	v_mov_b32_e32 v100, v0
	v_mov_b32_e32 v101, v0
	v_mov_b32_e32 v102, v0
	v_mov_b32_e32 v103, v0
	v_mov_b32_e32 v104, v0
	v_mov_b32_e32 v105, v0
	v_mov_b32_e32 v114, v0
	v_mov_b32_e32 v115, v0
	v_mov_b32_e32 v116, v0
	v_mov_b32_e32 v117, v0
	v_mov_b32_e32 v118, v0
	v_mov_b32_e32 v119, v0
	v_mov_b32_e32 v120, v0
	v_mov_b32_e32 v121, v0
	v_mov_b32_e32 v74, v0
	v_mov_b32_e32 v75, v0
	v_mov_b32_e32 v76, v0
	v_mov_b32_e32 v77, v0
	v_mov_b32_e32 v78, v0
	v_mov_b32_e32 v79, v0
	v_mov_b32_e32 v80, v0
	v_mov_b32_e32 v81, v0
	v_mov_b32_e32 v90, v0
	v_mov_b32_e32 v91, v0
	v_mov_b32_e32 v92, v0
	v_mov_b32_e32 v93, v0
	v_mov_b32_e32 v94, v0
	v_mov_b32_e32 v95, v0
	v_mov_b32_e32 v96, v0
	v_mov_b32_e32 v97, v0
	v_mov_b32_e32 v106, v0
	v_mov_b32_e32 v107, v0
	v_mov_b32_e32 v108, v0
	v_mov_b32_e32 v109, v0
	v_mov_b32_e32 v110, v0
	v_mov_b32_e32 v111, v0
	v_mov_b32_e32 v112, v0
	v_mov_b32_e32 v113, v0
	v_mov_b32_e32 v122, v0
	v_mov_b32_e32 v123, v0
	v_mov_b32_e32 v124, v0
	v_mov_b32_e32 v125, v0
	v_mov_b32_e32 v126, v0
	v_mov_b32_e32 v127, v0
	v_mov_b32_e32 v128, v0
	v_mov_b32_e32 v129, v0
	v_add_u32_e32 v131, 0x10000, v147
	.p2align	6

.LBB0_1055:
	s_add_i32 s17, s1, -2
	s_add_u32 s24, s24, 0x40080
	s_addc_u32 s25, s25, 0
	s_add_u32 s19, s28, 0x100
	v_mov_b32_e32 v0, 0
	s_mov_b32 s81, s57
	s_addc_u32 s27, s29, 0
	s_mov_b32 s28, 0
	v_mov_b32_e32 v1, v0
	v_mov_b32_e32 v2, v0
	v_mov_b32_e32 v3, v0
	v_mov_b32_e32 v4, v0
	v_mov_b32_e32 v5, v0
	v_mov_b32_e32 v6, v0
	v_mov_b32_e32 v7, v0
	v_mov_b32_e32 v8, v0
	v_mov_b32_e32 v9, v0
	v_mov_b32_e32 v10, v0
	v_mov_b32_e32 v11, v0
	v_mov_b32_e32 v12, v0
	v_mov_b32_e32 v13, v0
	v_mov_b32_e32 v14, v0
	v_mov_b32_e32 v15, v0
	v_mov_b32_e32 v24, v0
	v_mov_b32_e32 v25, v0
	v_mov_b32_e32 v26, v0
	v_mov_b32_e32 v27, v0
	v_mov_b32_e32 v28, v0
	v_mov_b32_e32 v29, v0
	v_mov_b32_e32 v30, v0
	v_mov_b32_e32 v31, v0
	v_mov_b32_e32 v40, v0
	v_mov_b32_e32 v41, v0
	v_mov_b32_e32 v42, v0
	v_mov_b32_e32 v43, v0
	v_mov_b32_e32 v44, v0
	v_mov_b32_e32 v45, v0
	v_mov_b32_e32 v46, v0
	v_mov_b32_e32 v47, v0
	v_mov_b32_e32 v16, v0
	v_mov_b32_e32 v17, v0
	v_mov_b32_e32 v18, v0
	v_mov_b32_e32 v19, v0
	v_mov_b32_e32 v20, v0
	v_mov_b32_e32 v21, v0
	v_mov_b32_e32 v22, v0
	v_mov_b32_e32 v23, v0
	v_mov_b32_e32 v32, v0
	v_mov_b32_e32 v33, v0
	v_mov_b32_e32 v34, v0
	v_mov_b32_e32 v35, v0
	v_mov_b32_e32 v36, v0
	v_mov_b32_e32 v37, v0
	v_mov_b32_e32 v38, v0
	v_mov_b32_e32 v39, v0
	s_waitcnt vmcnt(0)
	v_mov_b32_e32 v50, v0
	v_mov_b32_e32 v51, v0
	v_mov_b32_e32 v52, v0
	v_mov_b32_e32 v53, v0
	v_mov_b32_e32 v54, v0
	v_mov_b32_e32 v55, v0
	v_mov_b32_e32 v56, v0
	v_mov_b32_e32 v57, v0
	v_mov_b32_e32 v58, v0
	v_mov_b32_e32 v59, v0
	v_mov_b32_e32 v60, v0
	v_mov_b32_e32 v61, v0
	v_mov_b32_e32 v62, v0
	v_mov_b32_e32 v63, v0
	v_mov_b32_e32 v64, v0
	v_mov_b32_e32 v65, v0
	v_mov_b32_e32 v66, v0
	v_mov_b32_e32 v67, v0
	v_mov_b32_e32 v68, v0
	v_mov_b32_e32 v69, v0
	v_mov_b32_e32 v70, v0
	v_mov_b32_e32 v71, v0
	v_mov_b32_e32 v72, v0
	v_mov_b32_e32 v73, v0
	v_mov_b32_e32 v74, v0
	v_mov_b32_e32 v75, v0
	v_mov_b32_e32 v76, v0
	v_mov_b32_e32 v77, v0
	v_mov_b32_e32 v78, v0
	v_mov_b32_e32 v79, v0
	v_mov_b32_e32 v80, v0
	v_mov_b32_e32 v81, v0
	v_mov_b32_e32 v90, v0
	v_mov_b32_e32 v91, v0
	v_mov_b32_e32 v92, v0
	v_mov_b32_e32 v93, v0
	v_mov_b32_e32 v94, v0
	v_mov_b32_e32 v95, v0
	v_mov_b32_e32 v96, v0
	v_mov_b32_e32 v97, v0
	v_mov_b32_e32 v106, v0
	v_mov_b32_e32 v107, v0
	v_mov_b32_e32 v108, v0
	v_mov_b32_e32 v109, v0
	v_mov_b32_e32 v110, v0
	v_mov_b32_e32 v111, v0
	v_mov_b32_e32 v112, v0
	v_mov_b32_e32 v113, v0
	v_mov_b32_e32 v82, v0
	v_mov_b32_e32 v83, v0
	v_mov_b32_e32 v84, v0
	v_mov_b32_e32 v85, v0
	v_mov_b32_e32 v86, v0
	v_mov_b32_e32 v87, v0
	v_mov_b32_e32 v88, v0
	v_mov_b32_e32 v89, v0
	v_mov_b32_e32 v98, v0
	v_mov_b32_e32 v99, v0
	v_mov_b32_e32 v100, v0
	v_mov_b32_e32 v101, v0
	v_mov_b32_e32 v102, v0
	v_mov_b32_e32 v103, v0
	v_mov_b32_e32 v104, v0
	v_mov_b32_e32 v105, v0
	v_mov_b32_e32 v114, v0
	v_mov_b32_e32 v115, v0
	v_mov_b32_e32 v116, v0
	v_mov_b32_e32 v117, v0
	v_mov_b32_e32 v118, v0
	v_mov_b32_e32 v119, v0
	v_mov_b32_e32 v120, v0
	v_mov_b32_e32 v121, v0
	v_mov_b32_e32 v122, v0
	v_mov_b32_e32 v123, v0
	v_mov_b32_e32 v124, v0
	v_mov_b32_e32 v125, v0
	v_mov_b32_e32 v126, v0
	v_mov_b32_e32 v127, v0
	v_mov_b32_e32 v128, v0
	v_mov_b32_e32 v129, v0
	v_add_u32_e32 v203, 0x10000, v216
	.p2align	6

.LBB0_1201:
	s_add_u32 s26, s26, 0x40080
	s_addc_u32 s27, s27, 0
	s_add_u32 s15, s28, 0x100
	v_mov_b32_e32 v0, 0
	s_addc_u32 s17, s29, 0
	s_mov_b32 s25, -2
	v_mov_b32_e32 v1, v0
	v_mov_b32_e32 v2, v0
	v_mov_b32_e32 v3, v0
	v_mov_b32_e32 v4, v0
	v_mov_b32_e32 v5, v0
	v_mov_b32_e32 v6, v0
	v_mov_b32_e32 v7, v0
	v_mov_b32_e32 v12, v0
	v_mov_b32_e32 v13, v0
	v_mov_b32_e32 v14, v0
	v_mov_b32_e32 v15, v0
	v_mov_b32_e32 v20, v0
	v_mov_b32_e32 v21, v0
	v_mov_b32_e32 v22, v0
	v_mov_b32_e32 v23, v0
	v_mov_b32_e32 v28, v0
	v_mov_b32_e32 v29, v0
	v_mov_b32_e32 v30, v0
	v_mov_b32_e32 v31, v0
	v_mov_b32_e32 v36, v0
	v_mov_b32_e32 v37, v0
	v_mov_b32_e32 v38, v0
	v_mov_b32_e32 v39, v0
	v_mov_b32_e32 v44, v0
	v_mov_b32_e32 v45, v0
	v_mov_b32_e32 v46, v0
	v_mov_b32_e32 v47, v0
	v_mov_b32_e32 v54, v0
	v_mov_b32_e32 v55, v0
	v_mov_b32_e32 v56, v0
	v_mov_b32_e32 v57, v0
	v_mov_b32_e32 v8, v0
	v_mov_b32_e32 v9, v0
	v_mov_b32_e32 v10, v0
	v_mov_b32_e32 v11, v0
	v_mov_b32_e32 v16, v0
	v_mov_b32_e32 v17, v0
	v_mov_b32_e32 v18, v0
	v_mov_b32_e32 v19, v0
	v_mov_b32_e32 v24, v0
	v_mov_b32_e32 v25, v0
	v_mov_b32_e32 v26, v0
	v_mov_b32_e32 v27, v0
	v_mov_b32_e32 v32, v0
	v_mov_b32_e32 v33, v0
	v_mov_b32_e32 v34, v0
	v_mov_b32_e32 v35, v0
	v_mov_b32_e32 v40, v0
	v_mov_b32_e32 v41, v0
	v_mov_b32_e32 v42, v0
	v_mov_b32_e32 v43, v0
	v_mov_b32_e32 v50, v0
	v_mov_b32_e32 v51, v0
	v_mov_b32_e32 v52, v0
	v_mov_b32_e32 v53, v0
	v_mov_b32_e32 v58, v0
	v_mov_b32_e32 v59, v0
	v_mov_b32_e32 v60, v0
	v_mov_b32_e32 v61, v0
	v_mov_b32_e32 v62, v0
	v_mov_b32_e32 v63, v0
	v_mov_b32_e32 v64, v0
	v_mov_b32_e32 v65, v0
	v_mov_b32_e32 v66, v0
	v_mov_b32_e32 v67, v0
	v_mov_b32_e32 v68, v0
	v_mov_b32_e32 v69, v0
	v_mov_b32_e32 v70, v0
	v_mov_b32_e32 v71, v0
	v_mov_b32_e32 v72, v0
	v_mov_b32_e32 v73, v0
	v_mov_b32_e32 v78, v0
	v_mov_b32_e32 v79, v0
	v_mov_b32_e32 v80, v0
	v_mov_b32_e32 v81, v0
	v_mov_b32_e32 v86, v0
	v_mov_b32_e32 v87, v0
	v_mov_b32_e32 v88, v0
	v_mov_b32_e32 v89, v0
	v_mov_b32_e32 v98, v0
	v_mov_b32_e32 v99, v0
	v_mov_b32_e32 v100, v0
	v_mov_b32_e32 v101, v0
	v_mov_b32_e32 v102, v0
	v_mov_b32_e32 v103, v0
	v_mov_b32_e32 v104, v0
	v_mov_b32_e32 v105, v0
	v_mov_b32_e32 v110, v0
	v_mov_b32_e32 v111, v0
	v_mov_b32_e32 v112, v0
	v_mov_b32_e32 v113, v0
	v_mov_b32_e32 v118, v0
	v_mov_b32_e32 v119, v0
	v_mov_b32_e32 v120, v0
	v_mov_b32_e32 v121, v0
	v_mov_b32_e32 v74, v0
	v_mov_b32_e32 v75, v0
	v_mov_b32_e32 v76, v0
	v_mov_b32_e32 v77, v0
	v_mov_b32_e32 v82, v0
	v_mov_b32_e32 v83, v0
	v_mov_b32_e32 v84, v0
	v_mov_b32_e32 v85, v0
	v_mov_b32_e32 v90, v0
	v_mov_b32_e32 v91, v0
	v_mov_b32_e32 v92, v0
	v_mov_b32_e32 v93, v0
	v_mov_b32_e32 v94, v0
	v_mov_b32_e32 v95, v0
	v_mov_b32_e32 v96, v0
	v_mov_b32_e32 v97, v0
	v_mov_b32_e32 v106, v0
	v_mov_b32_e32 v107, v0
	v_mov_b32_e32 v108, v0
	v_mov_b32_e32 v109, v0
	v_mov_b32_e32 v114, v0
	v_mov_b32_e32 v115, v0
	v_mov_b32_e32 v116, v0
	v_mov_b32_e32 v117, v0
	v_mov_b32_e32 v122, v0
	v_mov_b32_e32 v123, v0
	v_mov_b32_e32 v124, v0
	v_mov_b32_e32 v125, v0
	v_mov_b32_e32 v126, v0
	v_mov_b32_e32 v127, v0
	v_mov_b32_e32 v128, v0
	v_mov_b32_e32 v129, v0
	v_add_u32_e32 v218, 0x10000, v170
	.p2align	6

.LBB0_1218:
	s_add_u32 s24, s24, 0x40080
	s_addc_u32 s25, s25, 0
	s_add_u32 s15, s26, 0x100
	v_mov_b32_e32 v0, 0
	s_addc_u32 s17, s27, 0
	s_mov_b32 s30, -2
	v_mov_b32_e32 v1, v0
	v_mov_b32_e32 v2, v0
	v_mov_b32_e32 v3, v0
	v_mov_b32_e32 v4, v0
	v_mov_b32_e32 v5, v0
	v_mov_b32_e32 v6, v0
	v_mov_b32_e32 v7, v0
	v_mov_b32_e32 v12, v0
	v_mov_b32_e32 v13, v0
	v_mov_b32_e32 v14, v0
	v_mov_b32_e32 v15, v0
	v_mov_b32_e32 v16, v0
	v_mov_b32_e32 v17, v0
	v_mov_b32_e32 v18, v0
	v_mov_b32_e32 v19, v0
	v_mov_b32_e32 v28, v0
	v_mov_b32_e32 v29, v0
	v_mov_b32_e32 v30, v0
	v_mov_b32_e32 v31, v0
	v_mov_b32_e32 v32, v0
	v_mov_b32_e32 v33, v0
	v_mov_b32_e32 v34, v0
	v_mov_b32_e32 v35, v0
	v_mov_b32_e32 v44, v0
	v_mov_b32_e32 v45, v0
	v_mov_b32_e32 v46, v0
	v_mov_b32_e32 v47, v0
	v_mov_b32_e32 v50, v0
	v_mov_b32_e32 v51, v0
	v_mov_b32_e32 v52, v0
	v_mov_b32_e32 v53, v0
	v_mov_b32_e32 v8, v0
	v_mov_b32_e32 v9, v0
	v_mov_b32_e32 v10, v0
	v_mov_b32_e32 v11, v0
	v_mov_b32_e32 v20, v0
	v_mov_b32_e32 v21, v0
	v_mov_b32_e32 v22, v0
	v_mov_b32_e32 v23, v0
	v_mov_b32_e32 v24, v0
	v_mov_b32_e32 v25, v0
	v_mov_b32_e32 v26, v0
	v_mov_b32_e32 v27, v0
	v_mov_b32_e32 v36, v0
	v_mov_b32_e32 v37, v0
	v_mov_b32_e32 v38, v0
	v_mov_b32_e32 v39, v0
	v_mov_b32_e32 v40, v0
	v_mov_b32_e32 v41, v0
	v_mov_b32_e32 v42, v0
	v_mov_b32_e32 v43, v0
	v_mov_b32_e32 v54, v0
	v_mov_b32_e32 v55, v0
	v_mov_b32_e32 v56, v0
	v_mov_b32_e32 v57, v0
	v_mov_b32_e32 v58, v0
	v_mov_b32_e32 v59, v0
	v_mov_b32_e32 v60, v0
	v_mov_b32_e32 v61, v0
	v_mov_b32_e32 v62, v0
	v_mov_b32_e32 v63, v0
	v_mov_b32_e32 v64, v0
	v_mov_b32_e32 v65, v0
	v_mov_b32_e32 v66, v0
	v_mov_b32_e32 v67, v0
	v_mov_b32_e32 v68, v0
	v_mov_b32_e32 v69, v0
	v_mov_b32_e32 v70, v0
	v_mov_b32_e32 v71, v0
	v_mov_b32_e32 v72, v0
	v_mov_b32_e32 v73, v0
	v_mov_b32_e32 v78, v0
	v_mov_b32_e32 v79, v0
	v_mov_b32_e32 v80, v0
	v_mov_b32_e32 v81, v0
	v_mov_b32_e32 v82, v0
	v_mov_b32_e32 v83, v0
	v_mov_b32_e32 v84, v0
	v_mov_b32_e32 v85, v0
	v_mov_b32_e32 v98, v0
	v_mov_b32_e32 v99, v0
	v_mov_b32_e32 v100, v0
	v_mov_b32_e32 v101, v0
	v_mov_b32_e32 v102, v0
	v_mov_b32_e32 v103, v0
	v_mov_b32_e32 v104, v0
	v_mov_b32_e32 v105, v0
	v_mov_b32_e32 v110, v0
	v_mov_b32_e32 v111, v0
	v_mov_b32_e32 v112, v0
	v_mov_b32_e32 v113, v0
	v_mov_b32_e32 v114, v0
	v_mov_b32_e32 v115, v0
	v_mov_b32_e32 v116, v0
	v_mov_b32_e32 v117, v0
	v_mov_b32_e32 v74, v0
	v_mov_b32_e32 v75, v0
	v_mov_b32_e32 v76, v0
	v_mov_b32_e32 v77, v0
	v_mov_b32_e32 v86, v0
	v_mov_b32_e32 v87, v0
	v_mov_b32_e32 v88, v0
	v_mov_b32_e32 v89, v0
	v_mov_b32_e32 v90, v0
	v_mov_b32_e32 v91, v0
	v_mov_b32_e32 v92, v0
	v_mov_b32_e32 v93, v0
	v_mov_b32_e32 v94, v0
	v_mov_b32_e32 v95, v0
	v_mov_b32_e32 v96, v0
	v_mov_b32_e32 v97, v0
	v_mov_b32_e32 v106, v0
	v_mov_b32_e32 v107, v0
	v_mov_b32_e32 v108, v0
	v_mov_b32_e32 v109, v0
	v_mov_b32_e32 v118, v0
	v_mov_b32_e32 v119, v0
	v_mov_b32_e32 v120, v0
	v_mov_b32_e32 v121, v0
	v_mov_b32_e32 v122, v0
	v_mov_b32_e32 v123, v0
	v_mov_b32_e32 v124, v0
	v_mov_b32_e32 v125, v0
	v_mov_b32_e32 v126, v0
	v_mov_b32_e32 v127, v0
	v_mov_b32_e32 v128, v0
	v_mov_b32_e32 v129, v0
	v_add_u32_e32 v201, 0x10000, v208
	.p2align	6

.LBB0_1355:
	s_add_u32 s26, s26, 0x40080
	s_addc_u32 s27, s27, 0
	s_add_u32 s15, s28, 0x100
	v_mov_b32_e32 v0, 0
	s_addc_u32 s17, s29, 0
	s_mov_b32 s45, -2
	v_mov_b32_e32 v1, v0
	v_mov_b32_e32 v2, v0
	v_mov_b32_e32 v3, v0
	v_mov_b32_e32 v8, v0
	v_mov_b32_e32 v9, v0
	v_mov_b32_e32 v10, v0
	v_mov_b32_e32 v11, v0
	v_mov_b32_e32 v16, v0
	v_mov_b32_e32 v17, v0
	v_mov_b32_e32 v18, v0
	v_mov_b32_e32 v19, v0
	v_mov_b32_e32 v24, v0
	v_mov_b32_e32 v25, v0
	v_mov_b32_e32 v26, v0
	v_mov_b32_e32 v27, v0
	v_mov_b32_e32 v32, v0
	v_mov_b32_e32 v33, v0
	v_mov_b32_e32 v34, v0
	v_mov_b32_e32 v35, v0
	v_mov_b32_e32 v40, v0
	v_mov_b32_e32 v41, v0
	v_mov_b32_e32 v42, v0
	v_mov_b32_e32 v43, v0
	v_mov_b32_e32 v50, v0
	v_mov_b32_e32 v51, v0
	v_mov_b32_e32 v52, v0
	v_mov_b32_e32 v53, v0
	v_mov_b32_e32 v58, v0
	v_mov_b32_e32 v59, v0
	v_mov_b32_e32 v60, v0
	v_mov_b32_e32 v61, v0
	v_mov_b32_e32 v4, v0
	v_mov_b32_e32 v5, v0
	v_mov_b32_e32 v6, v0
	v_mov_b32_e32 v7, v0
	v_mov_b32_e32 v12, v0
	v_mov_b32_e32 v13, v0
	v_mov_b32_e32 v14, v0
	v_mov_b32_e32 v15, v0
	v_mov_b32_e32 v20, v0
	v_mov_b32_e32 v21, v0
	v_mov_b32_e32 v22, v0
	v_mov_b32_e32 v23, v0
	v_mov_b32_e32 v28, v0
	v_mov_b32_e32 v29, v0
	v_mov_b32_e32 v30, v0
	v_mov_b32_e32 v31, v0
	v_mov_b32_e32 v36, v0
	v_mov_b32_e32 v37, v0
	v_mov_b32_e32 v38, v0
	v_mov_b32_e32 v39, v0
	v_mov_b32_e32 v44, v0
	v_mov_b32_e32 v45, v0
	v_mov_b32_e32 v46, v0
	v_mov_b32_e32 v47, v0
	v_mov_b32_e32 v54, v0
	v_mov_b32_e32 v55, v0
	v_mov_b32_e32 v56, v0
	v_mov_b32_e32 v57, v0
	v_mov_b32_e32 v62, v0
	v_mov_b32_e32 v63, v0
	v_mov_b32_e32 v64, v0
	v_mov_b32_e32 v65, v0
	v_mov_b32_e32 v66, v0
	v_mov_b32_e32 v67, v0
	v_mov_b32_e32 v68, v0
	v_mov_b32_e32 v69, v0
	v_mov_b32_e32 v74, v0
	v_mov_b32_e32 v75, v0
	v_mov_b32_e32 v76, v0
	v_mov_b32_e32 v77, v0
	v_mov_b32_e32 v82, v0
	v_mov_b32_e32 v83, v0
	v_mov_b32_e32 v84, v0
	v_mov_b32_e32 v85, v0
	v_mov_b32_e32 v90, v0
	v_mov_b32_e32 v91, v0
	v_mov_b32_e32 v92, v0
	v_mov_b32_e32 v93, v0
	v_mov_b32_e32 v98, v0
	v_mov_b32_e32 v99, v0
	v_mov_b32_e32 v100, v0
	v_mov_b32_e32 v101, v0
	v_mov_b32_e32 v106, v0
	v_mov_b32_e32 v107, v0
	v_mov_b32_e32 v108, v0
	v_mov_b32_e32 v109, v0
	v_mov_b32_e32 v114, v0
	v_mov_b32_e32 v115, v0
	v_mov_b32_e32 v116, v0
	v_mov_b32_e32 v117, v0
	v_mov_b32_e32 v122, v0
	v_mov_b32_e32 v123, v0
	v_mov_b32_e32 v124, v0
	v_mov_b32_e32 v125, v0
	v_mov_b32_e32 v70, v0
	v_mov_b32_e32 v71, v0
	v_mov_b32_e32 v72, v0
	v_mov_b32_e32 v73, v0
	v_mov_b32_e32 v78, v0
	v_mov_b32_e32 v79, v0
	v_mov_b32_e32 v80, v0
	v_mov_b32_e32 v81, v0
	v_mov_b32_e32 v86, v0
	v_mov_b32_e32 v87, v0
	v_mov_b32_e32 v88, v0
	v_mov_b32_e32 v89, v0
	v_mov_b32_e32 v94, v0
	v_mov_b32_e32 v95, v0
	v_mov_b32_e32 v96, v0
	v_mov_b32_e32 v97, v0
	v_mov_b32_e32 v102, v0
	v_mov_b32_e32 v103, v0
	v_mov_b32_e32 v104, v0
	v_mov_b32_e32 v105, v0
	v_mov_b32_e32 v110, v0
	v_mov_b32_e32 v111, v0
	v_mov_b32_e32 v112, v0
	v_mov_b32_e32 v113, v0
	v_mov_b32_e32 v118, v0
	v_mov_b32_e32 v119, v0
	v_mov_b32_e32 v120, v0
	v_mov_b32_e32 v121, v0
	v_mov_b32_e32 v126, v0
	v_mov_b32_e32 v127, v0
	v_mov_b32_e32 v128, v0
	v_mov_b32_e32 v129, v0
	v_add_u32_e32 v137, 0x10000, v143
	.p2align	6

.LBB0_1420:
	s_add_u32 s44, s18, 0x100
	v_mov_b32_e32 v0, 0
	s_addc_u32 s45, s19, 0
	s_mov_b32 s46, -2
	v_mov_b32_e32 v1, v0
	v_mov_b32_e32 v2, v0
	v_mov_b32_e32 v3, v0
	v_mov_b32_e32 v4, v0
	v_mov_b32_e32 v5, v0
	v_mov_b32_e32 v6, v0
	v_mov_b32_e32 v7, v0
	v_mov_b32_e32 v12, v0
	v_mov_b32_e32 v13, v0
	v_mov_b32_e32 v14, v0
	v_mov_b32_e32 v15, v0
	v_mov_b32_e32 v20, v0
	v_mov_b32_e32 v21, v0
	v_mov_b32_e32 v22, v0
	v_mov_b32_e32 v23, v0
	v_mov_b32_e32 v28, v0
	v_mov_b32_e32 v29, v0
	v_mov_b32_e32 v30, v0
	v_mov_b32_e32 v31, v0
	v_mov_b32_e32 v36, v0
	v_mov_b32_e32 v37, v0
	v_mov_b32_e32 v38, v0
	v_mov_b32_e32 v39, v0
	v_mov_b32_e32 v44, v0
	v_mov_b32_e32 v45, v0
	v_mov_b32_e32 v46, v0
	v_mov_b32_e32 v47, v0
	v_mov_b32_e32 v54, v0
	v_mov_b32_e32 v55, v0
	v_mov_b32_e32 v56, v0
	v_mov_b32_e32 v57, v0
	v_mov_b32_e32 v8, v0
	v_mov_b32_e32 v9, v0
	v_mov_b32_e32 v10, v0
	v_mov_b32_e32 v11, v0
	v_mov_b32_e32 v16, v0
	v_mov_b32_e32 v17, v0
	v_mov_b32_e32 v18, v0
	v_mov_b32_e32 v19, v0
	v_mov_b32_e32 v24, v0
	v_mov_b32_e32 v25, v0
	v_mov_b32_e32 v26, v0
	v_mov_b32_e32 v27, v0
	v_mov_b32_e32 v32, v0
	v_mov_b32_e32 v33, v0
	v_mov_b32_e32 v34, v0
	v_mov_b32_e32 v35, v0
	v_mov_b32_e32 v40, v0
	v_mov_b32_e32 v41, v0
	v_mov_b32_e32 v42, v0
	v_mov_b32_e32 v43, v0
	v_mov_b32_e32 v50, v0
	v_mov_b32_e32 v51, v0
	v_mov_b32_e32 v52, v0
	v_mov_b32_e32 v53, v0
	v_mov_b32_e32 v58, v0
	v_mov_b32_e32 v59, v0
	v_mov_b32_e32 v60, v0
	v_mov_b32_e32 v61, v0
	v_mov_b32_e32 v62, v0
	v_mov_b32_e32 v63, v0
	v_mov_b32_e32 v64, v0
	v_mov_b32_e32 v65, v0
	v_mov_b32_e32 v66, v0
	v_mov_b32_e32 v67, v0
	v_mov_b32_e32 v68, v0
	v_mov_b32_e32 v69, v0
	v_mov_b32_e32 v70, v0
	v_mov_b32_e32 v71, v0
	v_mov_b32_e32 v72, v0
	v_mov_b32_e32 v73, v0
	v_mov_b32_e32 v78, v0
	v_mov_b32_e32 v79, v0
	v_mov_b32_e32 v80, v0
	v_mov_b32_e32 v81, v0
	v_mov_b32_e32 v86, v0
	v_mov_b32_e32 v87, v0
	v_mov_b32_e32 v88, v0
	v_mov_b32_e32 v89, v0
	v_mov_b32_e32 v94, v0
	v_mov_b32_e32 v95, v0
	v_mov_b32_e32 v96, v0
	v_mov_b32_e32 v97, v0
	v_mov_b32_e32 v102, v0
	v_mov_b32_e32 v103, v0
	v_mov_b32_e32 v104, v0
	v_mov_b32_e32 v105, v0
	v_mov_b32_e32 v110, v0
	v_mov_b32_e32 v111, v0
	v_mov_b32_e32 v112, v0
	v_mov_b32_e32 v113, v0
	v_mov_b32_e32 v118, v0
	v_mov_b32_e32 v119, v0
	v_mov_b32_e32 v120, v0
	v_mov_b32_e32 v121, v0
	v_mov_b32_e32 v74, v0
	v_mov_b32_e32 v75, v0
	v_mov_b32_e32 v76, v0
	v_mov_b32_e32 v77, v0
	v_mov_b32_e32 v82, v0
	v_mov_b32_e32 v83, v0
	v_mov_b32_e32 v84, v0
	v_mov_b32_e32 v85, v0
	v_mov_b32_e32 v90, v0
	v_mov_b32_e32 v91, v0
	v_mov_b32_e32 v92, v0
	v_mov_b32_e32 v93, v0
	v_mov_b32_e32 v98, v0
	v_mov_b32_e32 v99, v0
	v_mov_b32_e32 v100, v0
	v_mov_b32_e32 v101, v0
	v_mov_b32_e32 v106, v0
	v_mov_b32_e32 v107, v0
	v_mov_b32_e32 v108, v0
	v_mov_b32_e32 v109, v0
	v_mov_b32_e32 v114, v0
	v_mov_b32_e32 v115, v0
	v_mov_b32_e32 v116, v0
	v_mov_b32_e32 v117, v0
	v_mov_b32_e32 v122, v0
	v_mov_b32_e32 v123, v0
	v_mov_b32_e32 v124, v0
	v_mov_b32_e32 v125, v0
	v_mov_b32_e32 v126, v0
	v_mov_b32_e32 v127, v0
	v_mov_b32_e32 v128, v0
	v_mov_b32_e32 v129, v0
	v_add_u32_e32 v202, 0x10000, v204
	.p2align	6

.LBB0_1434:
	s_add_u32 s44, s20, 0x100
	v_mov_b32_e32 v0, 0
	s_addc_u32 s45, s21, 0
	s_mov_b32 s46, -2
	v_mov_b32_e32 v1, v0
	v_mov_b32_e32 v2, v0
	v_mov_b32_e32 v3, v0
	v_mov_b32_e32 v4, v0
	v_mov_b32_e32 v5, v0
	v_mov_b32_e32 v6, v0
	v_mov_b32_e32 v7, v0
	v_mov_b32_e32 v12, v0
	v_mov_b32_e32 v13, v0
	v_mov_b32_e32 v14, v0
	v_mov_b32_e32 v15, v0
	v_mov_b32_e32 v20, v0
	v_mov_b32_e32 v21, v0
	v_mov_b32_e32 v22, v0
	v_mov_b32_e32 v23, v0
	v_mov_b32_e32 v28, v0
	v_mov_b32_e32 v29, v0
	v_mov_b32_e32 v30, v0
	v_mov_b32_e32 v31, v0
	v_mov_b32_e32 v36, v0
	v_mov_b32_e32 v37, v0
	v_mov_b32_e32 v38, v0
	v_mov_b32_e32 v39, v0
	v_mov_b32_e32 v44, v0
	v_mov_b32_e32 v45, v0
	v_mov_b32_e32 v46, v0
	v_mov_b32_e32 v47, v0
	v_mov_b32_e32 v54, v0
	v_mov_b32_e32 v55, v0
	v_mov_b32_e32 v56, v0
	v_mov_b32_e32 v57, v0
	v_mov_b32_e32 v8, v0
	v_mov_b32_e32 v9, v0
	v_mov_b32_e32 v10, v0
	v_mov_b32_e32 v11, v0
	v_mov_b32_e32 v16, v0
	v_mov_b32_e32 v17, v0
	v_mov_b32_e32 v18, v0
	v_mov_b32_e32 v19, v0
	v_mov_b32_e32 v24, v0
	v_mov_b32_e32 v25, v0
	v_mov_b32_e32 v26, v0
	v_mov_b32_e32 v27, v0
	v_mov_b32_e32 v32, v0
	v_mov_b32_e32 v33, v0
	v_mov_b32_e32 v34, v0
	v_mov_b32_e32 v35, v0
	v_mov_b32_e32 v40, v0
	v_mov_b32_e32 v41, v0
	v_mov_b32_e32 v42, v0
	v_mov_b32_e32 v43, v0
	v_mov_b32_e32 v50, v0
	v_mov_b32_e32 v51, v0
	v_mov_b32_e32 v52, v0
	v_mov_b32_e32 v53, v0
	v_mov_b32_e32 v58, v0
	v_mov_b32_e32 v59, v0
	v_mov_b32_e32 v60, v0
	v_mov_b32_e32 v61, v0
	v_mov_b32_e32 v62, v0
	v_mov_b32_e32 v63, v0
	v_mov_b32_e32 v64, v0
	v_mov_b32_e32 v65, v0
	v_mov_b32_e32 v66, v0
	v_mov_b32_e32 v67, v0
	v_mov_b32_e32 v68, v0
	v_mov_b32_e32 v69, v0
	v_mov_b32_e32 v70, v0
	v_mov_b32_e32 v71, v0
	v_mov_b32_e32 v72, v0
	v_mov_b32_e32 v73, v0
	v_mov_b32_e32 v78, v0
	v_mov_b32_e32 v79, v0
	v_mov_b32_e32 v80, v0
	v_mov_b32_e32 v81, v0
	v_mov_b32_e32 v86, v0
	v_mov_b32_e32 v87, v0
	v_mov_b32_e32 v88, v0
	v_mov_b32_e32 v89, v0
	v_mov_b32_e32 v94, v0
	v_mov_b32_e32 v95, v0
	v_mov_b32_e32 v96, v0
	v_mov_b32_e32 v97, v0
	v_mov_b32_e32 v102, v0
	v_mov_b32_e32 v103, v0
	v_mov_b32_e32 v104, v0
	v_mov_b32_e32 v105, v0
	v_mov_b32_e32 v110, v0
	v_mov_b32_e32 v111, v0
	v_mov_b32_e32 v112, v0
	v_mov_b32_e32 v113, v0
	v_mov_b32_e32 v118, v0
	v_mov_b32_e32 v119, v0
	v_mov_b32_e32 v120, v0
	v_mov_b32_e32 v121, v0
	v_mov_b32_e32 v74, v0
	v_mov_b32_e32 v75, v0
	v_mov_b32_e32 v76, v0
	v_mov_b32_e32 v77, v0
	v_mov_b32_e32 v82, v0
	v_mov_b32_e32 v83, v0
	v_mov_b32_e32 v84, v0
	v_mov_b32_e32 v85, v0
	v_mov_b32_e32 v90, v0
	v_mov_b32_e32 v91, v0
	v_mov_b32_e32 v92, v0
	v_mov_b32_e32 v93, v0
	v_mov_b32_e32 v98, v0
	v_mov_b32_e32 v99, v0
	v_mov_b32_e32 v100, v0
	v_mov_b32_e32 v101, v0
	v_mov_b32_e32 v106, v0
	v_mov_b32_e32 v107, v0
	v_mov_b32_e32 v108, v0
	v_mov_b32_e32 v109, v0
	v_mov_b32_e32 v114, v0
	v_mov_b32_e32 v115, v0
	v_mov_b32_e32 v116, v0
	v_mov_b32_e32 v117, v0
	v_mov_b32_e32 v122, v0
	v_mov_b32_e32 v123, v0
	v_mov_b32_e32 v124, v0
	v_mov_b32_e32 v125, v0
	v_mov_b32_e32 v126, v0
	v_mov_b32_e32 v127, v0
	v_mov_b32_e32 v128, v0
	v_mov_b32_e32 v129, v0
	v_add_u32_e32 v214, 0x10000, v242
	.p2align	6
